# P7 chunk-out: per-item v/gate/gw/gb operands prefetched one item ahead; item-end vmcnt(0) -> vmcnt(8) (own stores stay in flight); first trip still waits for the preamble's operand loads; on top of al
# speedup vs baseline: 1.0067x; 1.0067x over previous
; #define GAS __attribute__((address_space(1)))
; #define LAS __attribute__((address_space(3)))
; __device__ __forceinline__ void chunk_out_load(Frame& F, int item, ChunkOutOps& o, int w, int fr, int fq) {
;     const bf16* S = (const bf16*)(F.ws + WS_S) + (size_t)item * 4096; const bf16* RP = (const bf16*)(F.ws + WS_RP) + (size_t)item * 4096; const bf16* Y0 = (const bf16*)(F.ws + WS_Y0) + (size_t)item * 4096;
; #pragma unroll
;     for (int q = 0; q < 2; ++q) { const int tw = 2 * w + q, p0 = 16 * (tw >> 2), q0 = 16 * (tw & 3);
;         o.y0[q] = *(const GAS v2u*)(Y0 + (p0 + fr) * 64 + q0 + 4 * fq);
; #pragma unroll
;         for (int k = 0; k < 2; ++k) { o.sf[q][k] = *(const GAS bf16x8*)(S + (q0 + fr) * 64 + k * 32 + fq * 8); o.rf[q][k] = *(const GAS bf16x8*)(RP + (p0 + fr) * 64 + k * 32 + fq * 8); } }
; }
; __device__ __forceinline__ void rwkv_chunk_out_all(Frame& F) {
;     const float* PRM = (const float*)(F.ws + WS_PRM);
;     LAS unsigned char* L = F.lds;
;     const int lane = F.lane, w = F.wave, fr = lane & 15, fq = lane >> 4;
;     ChunkOutOps cur, nxt;
;     int item = F.vcu;
;     if (item < NITEM) chunk_out_load(F, item, cur, w, fr, fq);
;     for (; item < NITEM; item += F.G) {
;         const int bh = item / NCH, c = item % NCH, b = bh / RW_H, h = bh % RW_H; const int row0 = b * T + c * CH;
;         const int ch = lane, gc = h * 64 + ch;
;         const bf16* VB = (const bf16*)(F.ws + WS_VB) + (size_t)item * 4096; const bf16* G = (const bf16*)(F.ws + WS_G) + (size_t)item * 4096;
;         const v4u vbq = *(const GAS v4u*)(VB + ch * 64 + 8 * w), ggq = *(const GAS v4u*)(G + ch * 64 + 8 * w);
;         const int inext = item + F.G;
;         if (inext < NITEM) chunk_out_load(F, inext, nxt, w, fr, fq);
; #pragma unroll
;         for (int q = 0; q < 2; ++q) { const int tw = 2 * w + q, p0 = 16 * (tw >> 2), q0 = 16 * (tw & 3);
;             f32x4 a = (f32x4){bflo(cur.y0[q].x), bfhi(cur.y0[q].x), bflo(cur.y0[q].y), bfhi(cur.y0[q].y)};
; #pragma unroll
;             for (int k = 0; k < 2; ++k) a = __builtin_amdgcn_mfma_f32_16x16x32_bf16(cur.sf[q][k], cur.rf[q][k], a, 0, 0, 0);
; #pragma unroll
;             for (int v = 0; v < 4; ++v) *(LAS float*)(L + L_YL + ((p0 + fr) * 65 + q0 + 4 * fq + v) * 4) = a[v];
;         }
;         LBAR();
;         {
;             const float gw = (PRM + 4608)[gc], gb = (PRM + 5120)[gc];
.LBB0_1673:
	s_load_dwordx2 s[2:3], s[72:73], 0x108
	s_waitcnt lgkmcnt(0)
	s_cmp_lt_i32 s2, 8
	s_cselect_b64 s[0:1], -1, 0
	s_cmp_gt_i32 s3, 7
	s_cselect_b64 s[2:3], -1, 0
	s_and_b64 s[0:1], s[0:1], s[2:3]
	s_andn2_b64 vcc, exec, s[0:1]
	s_cbranch_vccnz .LBB0_1716
	v_readlane_b32 s0, v254, 2
	s_cmpk_gt_i32 s0, 0x7ff
	v_readlane_b32 s1, v254, 3
	s_cbranch_scc1 .LBB0_1679
	s_add_u32 s6, s86, 0x200000
	s_addc_u32 s7, s87, 0
	s_add_u32 s10, s86, 0xe000000
	s_addc_u32 s11, s87, 0
	s_add_u32 s12, s86, 0xf000000
	s_addc_u32 s13, s87, 0
	s_lshl_b32 s0, s93, 5
	s_lshl_b32 s18, s93, 3
	s_and_b32 s19, s0, 32
	s_and_b32 s1, s18, 0x1ffffff0
	s_or_b32 s20, s19, 16
	v_and_b32_e32 v4, 15, v208
	s_add_u32 s0, s86, 0x14800
	v_or_b32_e32 v20, s1, v4
	s_addc_u32 s1, s87, 0
	s_add_u32 s2, s86, 0x15000
	s_addc_u32 s3, s87, 0
	s_lshl_b32 s8, s93, 4
	v_readlane_b32 s22, v254, 2
	s_add_u32 s4, s86, 0x7000000
	v_readlane_b32 s23, v254, 3
	s_addc_u32 s5, s87, 0
	s_ashr_i32 s23, s22, 31
	s_lshl_b64 s[14:15], s[22:23], 13
	v_or_b32_e32 v21, s19, v4
	v_or_b32_e32 v22, s20, v4
	v_lshlrev_b32_e32 v4, 6, v208
	s_add_u32 s16, s6, s14
	v_mov_b32_e32 v57, 0
	v_ashrrev_i32_e32 v5, 31, v4
	v_lshlrev_b32_e32 v56, 7, v20
	s_addc_u32 s17, s7, s15
	v_ashrrev_i32_e32 v2, 4, v208
	s_mov_b32 s9, 0
	v_lshl_add_u64 v[4:5], v[4:5], 1, s[86:87]
	v_lshl_add_u64 v[6:7], s[12:13], 0, v[56:57]
	s_add_u32 s12, s12, s14
	v_lshlrev_b32_e32 v0, 2, v2
	v_lshlrev_b32_e32 v2, 3, v2
	v_lshl_add_u64 v[4:5], v[4:5], 0, s[8:9]
	s_addc_u32 s13, s13, s15
	s_lshl_b32 s8, s19, 1
	v_ashrrev_i32_e32 v3, 31, v2
	v_lshl_add_u64 v[10:11], s[10:11], 0, v[56:57]
	s_add_u32 s10, s10, s14
	v_ashrrev_i32_e32 v1, 31, v0
	v_lshlrev_b64 v[2:3], 1, v[2:3]
	s_addc_u32 s11, s11, s15
	v_lshlrev_b64 v[8:9], 1, v[0:1]
	v_lshl_add_u64 v[12:13], s[16:17], 0, v[2:3]
	v_lshlrev_b32_e32 v14, 7, v22
	v_mov_b32_e32 v15, v57
	v_lshl_add_u64 v[16:17], s[12:13], 0, v[56:57]
	v_lshl_add_u64 v[18:19], s[10:11], 0, v[56:57]
	v_lshlrev_b32_e32 v56, 7, v21
	v_lshl_add_u64 v[14:15], v[12:13], 0, v[14:15]
	v_lshl_add_u64 v[16:17], v[16:17], 0, v[8:9]
	v_lshl_add_u64 v[12:13], v[12:13], 0, v[56:57]
	v_lshl_add_u64 v[16:17], v[16:17], 0, s[8:9]
	v_lshl_add_u64 v[18:19], v[18:19], 0, v[2:3]
	global_load_dwordx4 v[52:55], v[12:13], off
	global_load_dwordx4 v[48:51], v[12:13], off offset:64
	global_load_dwordx4 v[36:39], v[18:19], off
	global_load_dwordx4 v[32:35], v[18:19], off offset:64
	global_load_dwordx2 v[76:77], v[16:17], off
	global_load_dwordx2 v[74:75], v[16:17], off offset:32
	global_load_dwordx4 v[44:47], v[14:15], off
	global_load_dwordx4 v[40:43], v[14:15], off offset:64
	s_movk_i32 s10, 0x41
	v_mad_u64_u32 v[0:1], s[10:11], v20, s10, v[0:1]
	v_lshl_add_u64 v[62:63], s[6:7], 0, v[2:3]
	s_lshl_b32 s6, s22, 6
	s_mul_i32 s10, s93, 0x208
	s_add_i32 s6, s6, s18
	v_add_lshl_u32 v78, v208, s10, 2
	s_mov_b64 s[10:11], 0xc000000
	s_or_b32 s12, s6, 7
	s_mov_b32 s6, s22
	v_lshlrev_b32_e32 v12, 6, v21
	v_lshlrev_b32_e32 v14, 6, v22
	v_add_lshl_u32 v13, v0, s19, 2
	v_add_lshl_u32 v15, s20, v0, 2
	v_add_u32_e32 v16, 0x104, v78
	v_add_u32_e32 v17, 0x208, v78
	v_add_u32_e32 v18, 0x30c, v78
	v_add_u32_e32 v19, 0x410, v78
	v_add_u32_e32 v20, 0x514, v78
	v_add_u32_e32 v21, 0x618, v78
	v_add_u32_e32 v22, 0x71c, v78
	v_lshl_add_u64 v[58:59], v[4:5], 0, s[10:11]
	s_mov_b64 s[10:11], 0xd000000
	v_lshl_add_u64 v[0:1], v[6:7], 0, v[8:9]
	v_writelane_b32 v254, s6, 2
	v_lshl_add_u64 v[60:61], v[4:5], 0, s[10:11]
	v_lshl_add_u64 v[64:65], v[10:11], 0, v[2:3]
	v_lshl_add_u64 v[66:67], v[0:1], 0, s[8:9]
	s_lshl_b32 s13, s77, 6
	v_lshlrev_b32_e32 v56, 1, v12
	v_lshlrev_b32_e32 v68, 1, v14
	v_add_u32_e32 v79, 0, v13
	v_add_u32_e32 v80, 0, v15
	v_add_u32_e32 v81, 0, v16
	v_add_u32_e32 v82, 0, v17
	v_add_u32_e32 v83, 0, v18
	v_add_u32_e32 v84, 0, v19
	v_add_u32_e32 v85, 0, v20
	v_add_u32_e32 v86, 0, v21
	v_add_u32_e32 v87, 0, v22
	v_mov_b32_e32 v88, 0x3a27c5ac
	v_mov_b32_e32 v89, 0xbc800000
	v_mov_b32_e32 v90, 0x3c800000
	v_writelane_b32 v254, s7, 3
	s_mov_b32 s10, s22
	s_ashr_i32 s11, s10, 31
	s_lshl_b64 s[6:7], s[10:11], 13
	v_lshl_add_u64 v[92:93], v[58:59], 0, s[6:7]
	v_lshl_add_u64 v[94:95], v[60:61], 0, s[6:7]
	global_load_dwordx4 v[28:31], v[92:93], off
	global_load_dwordx4 v[24:27], v[94:95], off
	s_lshr_b32 s99, s10, 6
	s_and_b32 s99, s99, 7
	s_lshl_b32 s99, s99, 6
	v_add_lshl_u32 v96, v208, s99, 2
	v_mov_b32_e32 v97, 0
	v_lshl_add_u64 v[98:99], s[0:1], 0, v[96:97]
	v_lshl_add_u64 v[96:97], s[2:3], 0, v[96:97]
	global_load_dword v100, v[98:99], off
	global_load_dword v101, v[96:97], off
	s_mov_b32 s100, 1
	s_branch .LBB0_1677

; #define LAS __attribute__((address_space(3)))
; #define LBAR() asm volatile("s_waitcnt lgkmcnt(0)\n\ts_barrier" ::: "memory")
; __device__ __forceinline__ void rwkv_chunk_out_all(Frame& F) {
;     ...
; #pragma unroll
;         for (int q = 0; q < 2; ++q) { const int tw = 2 * w + q, p0 = 16 * (tw >> 2), q0 = 16 * (tw & 3);
;             f32x4 a = (f32x4){bflo(cur.y0[q].x), bfhi(cur.y0[q].x), bflo(cur.y0[q].y), bfhi(cur.y0[q].y)};
; #pragma unroll
;             for (int k = 0; k < 2; ++k) a = __builtin_amdgcn_mfma_f32_16x16x32_bf16(cur.sf[q][k], cur.rf[q][k], a, 0, 0, 0);
; #pragma unroll
;             for (int v = 0; v < 4; ++v) *(LAS float*)(L + L_YL + ((p0 + fr) * 65 + q0 + 4 * fq + v) * 4) = a[v];
;         }
;         LBAR();
;         {
;             const float gw = (PRM + 4608)[gc], gb = (PRM + 5120)[gc];
;             bf16* YM = (bf16*)(F.ws + WS_YMIX);
;             float yv[8], sm[8], sv[8];
; #pragma unroll
;             for (int tt = 0; tt < 8; ++tt) { yv[tt] = *(const LAS float*)(L + L_YL + ((8 * w + tt) * 65 + ch) * 4); sm[tt] = yv[tt]; }
;             wave_sum8(sm);
; #pragma unroll
;             for (int tt = 0; tt < 8; ++tt) { yv[tt] -= sm[tt] * (1.f / 64.f); sv[tt] = yv[tt] * yv[tt]; }
;             wave_sum8(sv);
.Lp7_body:
	v_lshlrev_b32_e32 v92, 16, v76
	v_and_b32_e32 v93, 0xffff0000, v76
	v_lshlrev_b32_e32 v94, 16, v77
	v_and_b32_e32 v95, 0xffff0000, v77
	s_lshr_b32 s7, s11, 26
	s_add_i32 s7, s10, s7
	v_mfma_f32_16x16x32_bf16 v[52:55], v[52:55], v[36:39], v[92:95]
	s_ashr_i32 s7, s7, 6
	s_lshr_b32 s11, s11, 23
	s_add_i32 s10, s10, s11
	v_mfma_f32_16x16x32_bf16 v[48:51], v[48:51], v[32:35], v[52:55]
	s_lshr_b32 s11, s7, 29
	s_add_i32 s11, s7, s11
	s_and_b32 s11, s11, 0x3fffff8
	s_nop 0
	v_lshlrev_b32_e32 v52, 16, v74
	v_and_b32_e32 v53, 0xffff0000, v74
	v_lshlrev_b32_e32 v54, 16, v75
	v_and_b32_e32 v55, 0xffff0000, v75
	s_sub_i32 s11, s7, s11
	ds_write2_b32 v79, v48, v49 offset1:1
	ds_write2_b32 v79, v50, v51 offset0:2 offset1:3
	v_mfma_f32_16x16x32_bf16 v[36:39], v[44:47], v[36:39], v[52:55]
	v_lshl_add_u32 v44, s11, 6, v208
	v_ashrrev_i32_e32 v45, 31, v44
	s_lshl_b32 s10, s10, 3
	v_mfma_f32_16x16x32_bf16 v[32:35], v[40:43], v[32:35], v[36:39]
	s_nop 7
	ds_write2_b32 v80, v32, v33 offset1:1
	ds_write2_b32 v80, v34, v35 offset0:2 offset1:3
	v_lshlrev_b64 v[32:33], 2, v[44:45]
	s_waitcnt lgkmcnt(0)
	s_barrier
	v_lshl_add_u64 v[34:35], s[0:1], 0, v[32:33]
	v_lshl_add_u64 v[32:33], s[2:3], 0, v[32:33]
	s_waitcnt vmcnt(12)
	v_mov_b32_e32 v36, v100
	v_mov_b32_e32 v37, v101
	v_add_u32_e32 v32, 0, v78
	ds_read_b32 v34, v32
	ds_read_b32 v38, v81
	ds_read_b32 v39, v82
	ds_read_b32 v40, v84
	ds_read_b32 v41, v83
	ds_read_b32 v42, v85
	ds_read_b32 v43, v86
	ds_read_b32 v46, v87
	s_waitcnt lgkmcnt(4)
	v_mov_b32_e32 v32, v40
	v_mov_b32_e32 v33, v34
	s_nop 1
	v_permlane32_swap_b32_e32 v33, v32
	v_add_f32_e32 v32, v33, v32
	s_waitcnt lgkmcnt(2)
	v_mov_b32_e32 v33, v42
	v_mov_b32_e32 v35, v38
	s_nop 1
	v_permlane32_swap_b32_e32 v35, v33
	v_add_f32_e32 v33, v35, v33
	v_mov_b32_e32 v35, v39
	s_waitcnt lgkmcnt(1)
	v_mov_b32_e32 v47, v43
	s_nop 1
	v_permlane32_swap_b32_e32 v35, v47
	v_add_f32_e32 v35, v35, v47
	s_nop 1
	v_permlane16_swap_b32_e32 v32, v35
	v_add_f32_e32 v32, v32, v35
	v_mov_b32_e32 v47, v41
	s_waitcnt lgkmcnt(0)
	v_mov_b32_e32 v48, v46
	v_add_f32_dpp v32, v32, v32 quad_perm:[1,0,3,2] row_mask:0xf bank_mask:0xf bound_ctrl:1
	s_nop 0
	v_permlane32_swap_b32_e32 v47, v48
	v_add_f32_dpp v32, v32, v32 quad_perm:[2,3,0,1] row_mask:0xf bank_mask:0xf bound_ctrl:1
	v_add_f32_e32 v47, v47, v48
	s_nop 1
	v_permlane16_swap_b32_e32 v33, v47
	v_add_f32_dpp v32, v32, v32 row_half_mirror row_mask:0xf bank_mask:0xf bound_ctrl:1
	v_add_f32_e32 v33, v33, v47
	s_and_b32 s10, s10, 0xfffff000
	v_add_f32_dpp v32, v32, v32 row_mirror row_mask:0xf bank_mask:0xf bound_ctrl:1
	v_add_f32_dpp v33, v33, v33 quad_perm:[1,0,3,2] row_mask:0xf bank_mask:0xf bound_ctrl:1
	v_readlane_b32 s11, v32, 0
	v_readlane_b32 s14, v32, 16
	v_readlane_b32 s15, v32, 32
	v_readlane_b32 s16, v32, 48
	v_fmac_f32_e32 v34, s11, v89
	v_fmac_f32_e32 v39, s14, v89
	v_fmac_f32_e32 v40, s15, v89
	v_fmac_f32_e32 v43, s16, v89
	v_mul_f32_e32 v32, v34, v34
	v_mul_f32_e32 v35, v39, v39
	v_mul_f32_e32 v48, v40, v40
	v_mul_f32_e32 v50, v43, v43
	s_nop 0
	v_permlane32_swap_b32_e32 v32, v48
	v_permlane32_swap_b32_e32 v35, v50
	v_add_f32_e32 v32, v32, v48
	v_add_f32_e32 v35, v35, v50
	s_nop 1
	v_permlane16_swap_b32_e32 v32, v35
	v_add_f32_dpp v33, v33, v33 quad_perm:[2,3,0,1] row_mask:0xf bank_mask:0xf bound_ctrl:1
	v_add_f32_e32 v32, v32, v35
	s_lshl_b32 s7, s7, 12
	v_add_f32_dpp v33, v33, v33 row_half_mirror row_mask:0xf bank_mask:0xf bound_ctrl:1
	v_add_f32_dpp v32, v32, v32 quad_perm:[1,0,3,2] row_mask:0xf bank_mask:0xf bound_ctrl:1
	s_sub_i32 s7, s10, s7
	v_add_f32_dpp v33, v33, v33 row_mirror row_mask:0xf bank_mask:0xf bound_ctrl:1
	v_add_f32_dpp v32, v32, v32 quad_perm:[2,3,0,1] row_mask:0xf bank_mask:0xf bound_ctrl:1
	v_readlane_b32 s17, v33, 0
	v_readlane_b32 s18, v33, 16
	v_readlane_b32 s19, v33, 32
	v_readlane_b32 s20, v33, 48
	v_add_f32_dpp v32, v32, v32 row_half_mirror row_mask:0xf bank_mask:0xf bound_ctrl:1
	v_fmac_f32_e32 v38, s17, v89
	v_fmac_f32_e32 v41, s18, v89
	v_fmac_f32_e32 v42, s19, v89
	v_fmac_f32_e32 v46, s20, v89
	v_add_f32_dpp v32, v32, v32 row_mirror row_mask:0xf bank_mask:0xf bound_ctrl:1
	v_mul_f32_e32 v33, v38, v38
	v_mul_f32_e32 v47, v41, v41
	v_mul_f32_e32 v49, v42, v42
	v_mul_f32_e32 v51, v46, v46
	v_readlane_b32 s11, v32, 0
	v_permlane32_swap_b32_e32 v33, v49
	v_permlane32_swap_b32_e32 v47, v51
	v_readlane_b32 s16, v32, 16
	v_readlane_b32 s17, v32, 32
	v_readlane_b32 s18, v32, 48
	v_fma_f32 v32, s11, v90, v88
	v_add_f32_e32 v33, v33, v49
	v_add_f32_e32 v47, v47, v51
	v_rsq_f32_e32 v35, v32
	s_nop 0
	v_permlane16_swap_b32_e32 v33, v47
	v_add_f32_e32 v33, v33, v47
	v_mul_f32_e32 v34, v34, v35
	v_fma_f32 v34, v36, v34, v37
	v_add_f32_dpp v33, v33, v33 quad_perm:[1,0,3,2] row_mask:0xf bank_mask:0xf bound_ctrl:1
; __device__ __forceinline__ unsigned f2bf(float f) { return pk2(f, 0.f) & 0xffffu; }
; #define LBAR() asm volatile("s_waitcnt lgkmcnt(0)\n\ts_barrier" ::: "memory")
; __device__ __forceinline__ void rwkv_chunk_out_all(Frame& F) {
;     ...
; #pragma unroll
;             for (int tt = 0; tt < 8; ++tt) { const int t = 8 * w + tt;
;                 const float yn = yv[tt] * __builtin_amdgcn_rsqf(sv[tt] * (1.f / 64.f) + GN_EPS) * gw + gb;
;                 const float o = (yn + ((tt & 1) ? bfhi(vbq[tt >> 1]) : bflo(vbq[tt >> 1]))) * ((tt & 1) ? bfhi(ggq[tt >> 1]) : bflo(ggq[tt >> 1]));
;                 YM[(size_t)(row0 + t) * D + gc] = (bf16)f2bf(o); }
;         }
;         LBAR();
;         cur = nxt;
	v_lshlrev_b32_e32 v35, 16, v28
	v_add_f32_e32 v34, v34, v35
	v_add_f32_dpp v33, v33, v33 quad_perm:[2,3,0,1] row_mask:0xf bank_mask:0xf bound_ctrl:1
	v_lshlrev_b32_e32 v35, 16, v24
	v_mul_f32_e32 v34, v34, v35
	v_add_f32_dpp v33, v33, v33 row_half_mirror row_mask:0xf bank_mask:0xf bound_ctrl:1
	s_add_i32 s10, s12, s7
	s_add_i32 s14, s10, -7
	v_add_f32_dpp v33, v33, v33 row_mirror row_mask:0xf bank_mask:0xf bound_ctrl:1
	s_ashr_i32 s15, s14, 31
	v_readlane_b32 s19, v33, 0
	v_readlane_b32 s20, v33, 16
	v_readlane_b32 s21, v33, 32
	v_readlane_b32 s22, v33, 48
	v_lshl_add_u64 v[32:33], v[44:45], 1, s[4:5]
	v_cvt_pk_bf16_f32 v44, v34, s0
	v_fma_f32 v34, s19, v90, v88
	v_rsq_f32_e32 v45, v34
	s_lshl_b64 s[14:15], s[14:15], 11
	v_lshl_add_u64 v[34:35], v[32:33], 0, s[14:15]
	global_store_short v[34:35], v44, off
	v_mul_f32_e32 v34, v38, v45
	v_fma_f32 v34, v36, v34, v37
	v_and_b32_e32 v28, 0xffff0000, v28
	v_add_f32_e32 v28, v34, v28
	v_and_b32_e32 v24, 0xffff0000, v24
	v_mul_f32_e32 v24, v28, v24
	v_fma_f32 v28, s16, v90, v88
	s_add_i32 s14, s10, -6
	v_rsq_f32_e32 v28, v28
	s_ashr_i32 s15, s14, 31
	s_lshl_b64 s[14:15], s[14:15], 11
	v_cvt_pk_bf16_f32 v24, v24, s0
	v_lshl_add_u64 v[34:35], v[32:33], 0, s[14:15]
	global_store_short v[34:35], v24, off
	v_mul_f32_e32 v24, v39, v28
	v_fma_f32 v24, v36, v24, v37
	v_lshlrev_b32_e32 v28, 16, v29
	v_add_f32_e32 v24, v24, v28
	v_lshlrev_b32_e32 v28, 16, v25
	v_mul_f32_e32 v24, v24, v28
	v_fma_f32 v28, s20, v90, v88
	s_add_i32 s14, s10, -5
	v_rsq_f32_e32 v28, v28
	s_ashr_i32 s15, s14, 31
	s_lshl_b64 s[14:15], s[14:15], 11
	v_cvt_pk_bf16_f32 v24, v24, s0
	v_lshl_add_u64 v[34:35], v[32:33], 0, s[14:15]
	global_store_short v[34:35], v24, off
	v_mul_f32_e32 v24, v41, v28
	v_fma_f32 v24, v36, v24, v37
	v_and_b32_e32 v28, 0xffff0000, v29
	v_add_f32_e32 v24, v24, v28
	v_and_b32_e32 v25, 0xffff0000, v25
	v_mul_f32_e32 v24, v24, v25
	v_cvt_pk_bf16_f32 v28, v24, s0
	v_fma_f32 v24, s17, v90, v88
	s_add_i32 s14, s10, -4
	v_rsq_f32_e32 v29, v24
	s_ashr_i32 s15, s14, 31
	s_lshl_b64 s[14:15], s[14:15], 11
	v_lshl_add_u64 v[24:25], v[32:33], 0, s[14:15]
	global_store_short v[24:25], v28, off
	v_mul_f32_e32 v24, v40, v29
	v_fma_f32 v24, v36, v24, v37
	v_lshlrev_b32_e32 v25, 16, v30
	v_add_f32_e32 v24, v24, v25
	v_lshlrev_b32_e32 v25, 16, v26
	v_mul_f32_e32 v24, v24, v25
	v_cvt_pk_bf16_f32 v28, v24, s0
	v_fma_f32 v24, s21, v90, v88
	s_add_i32 s14, s10, -3
	v_rsq_f32_e32 v29, v24
	s_ashr_i32 s15, s14, 31
	s_lshl_b64 s[14:15], s[14:15], 11
	v_lshl_add_u64 v[24:25], v[32:33], 0, s[14:15]
	global_store_short v[24:25], v28, off
	v_mul_f32_e32 v24, v42, v29
	v_fma_f32 v24, v36, v24, v37
	v_and_b32_e32 v25, 0xffff0000, v30
	v_add_f32_e32 v24, v24, v25
	v_and_b32_e32 v25, 0xffff0000, v26
	v_mul_f32_e32 v24, v24, v25
	v_cvt_pk_bf16_f32 v26, v24, s0
	v_fma_f32 v24, s18, v90, v88
	s_add_i32 s14, s10, -2
	v_rsq_f32_e32 v28, v24
	s_ashr_i32 s15, s14, 31
	s_lshl_b64 s[14:15], s[14:15], 11
	v_lshl_add_u64 v[24:25], v[32:33], 0, s[14:15]
	global_store_short v[24:25], v26, off
	v_mul_f32_e32 v24, v43, v28
	v_fma_f32 v24, v36, v24, v37
	v_lshlrev_b32_e32 v25, 16, v31
	v_add_f32_e32 v24, v24, v25
	v_lshlrev_b32_e32 v25, 16, v27
	v_mul_f32_e32 v24, v24, v25
	v_cvt_pk_bf16_f32 v26, v24, s0
	v_fma_f32 v24, s22, v90, v88
	s_add_i32 s14, s10, -1
	v_rsq_f32_e32 v28, v24
	s_ashr_i32 s15, s14, 31
	s_lshl_b64 s[14:15], s[14:15], 11
	v_lshl_add_u64 v[24:25], v[32:33], 0, s[14:15]
	global_store_short v[24:25], v26, off
	v_mul_f32_e32 v24, v46, v28
	v_fmac_f32_e32 v37, v36, v24
	v_and_b32_e32 v24, 0xffff0000, v31
	v_add_f32_e32 v24, v37, v24
	v_and_b32_e32 v25, 0xffff0000, v27
	s_ashr_i32 s11, s10, 31
	v_mul_f32_e32 v24, v24, v25
	s_lshl_b64 s[10:11], s[10:11], 11
	v_cvt_pk_bf16_f32 v26, v24, s0
	v_lshl_add_u64 v[24:25], v[32:33], 0, s[10:11]
	global_store_short v[24:25], v26, off
	s_waitcnt lgkmcnt(0)
	s_barrier
	s_waitcnt vmcnt(8)
	v_mov_b64_e32 v[34:35], v[14:15]
	v_mov_b64_e32 v[38:39], v[10:11]
	v_mov_b64_e32 v[42:43], v[22:23]
	v_mov_b64_e32 v[46:47], v[18:19]
	v_mov_b64_e32 v[50:51], v[6:7]
	v_mov_b64_e32 v[54:55], v[2:3]
	s_add_i32 s12, s12, s13
	s_andn2_b64 vcc, exec, s[8:9]
	v_mov_b64_e32 v[32:33], v[12:13]
	v_mov_b64_e32 v[36:37], v[8:9]
	v_mov_b64_e32 v[40:41], v[20:21]
	v_mov_b64_e32 v[44:45], v[16:17]
	v_mov_b64_e32 v[48:49], v[4:5]
	v_mov_b64_e32 v[52:53], v[0:1]
	v_mov_b64_e32 v[74:75], v[72:73]
	v_mov_b64_e32 v[76:77], v[70:71]
	v_mov_b64_e32 v[28:29], v[104:105]
	v_mov_b64_e32 v[30:31], v[106:107]
	v_mov_b64_e32 v[24:25], v[108:109]
	v_mov_b64_e32 v[26:27], v[110:111]
	v_mov_b32_e32 v100, v112
	v_mov_b32_e32 v101, v113
	s_mov_b32 s10, s6
	s_cbranch_vccz .LBB0_1679
.LBB0_1677:
	s_ashr_i32 s11, s10, 31


; #define GAS __attribute__((address_space(1)))
; __device__ __forceinline__ void chunk_out_load(Frame& F, int item, ChunkOutOps& o, int w, int fr, int fq) {
;     const bf16* S = (const bf16*)(F.ws + WS_S) + (size_t)item * 4096; const bf16* RP = (const bf16*)(F.ws + WS_RP) + (size_t)item * 4096; const bf16* Y0 = (const bf16*)(F.ws + WS_Y0) + (size_t)item * 4096;
; #pragma unroll
;     for (int q = 0; q < 2; ++q) { const int tw = 2 * w + q, p0 = 16 * (tw >> 2), q0 = 16 * (tw & 3);
;         o.y0[q] = *(const GAS v2u*)(Y0 + (p0 + fr) * 64 + q0 + 4 * fq);
; #pragma unroll
;         for (int k = 0; k < 2; ++k) { o.sf[q][k] = *(const GAS bf16x8*)(S + (q0 + fr) * 64 + k * 32 + fq * 8); o.rf[q][k] = *(const GAS bf16x8*)(RP + (p0 + fr) * 64 + k * 32 + fq * 8); } }
; }
; __device__ __forceinline__ void rwkv_chunk_out_all(Frame& F) {
;     ...
;     for (; item < NITEM; item += F.G) {
;         const int bh = item / NCH, c = item % NCH, b = bh / RW_H, h = bh % RW_H; const int row0 = b * T + c * CH;
;         const int ch = lane, gc = h * 64 + ch;
;         const bf16* VB = (const bf16*)(F.ws + WS_VB) + (size_t)item * 4096; const bf16* G = (const bf16*)(F.ws + WS_G) + (size_t)item * 4096;
;         const v4u vbq = *(const GAS v4u*)(VB + ch * 64 + 8 * w), ggq = *(const GAS v4u*)(G + ch * 64 + 8 * w);
;         const int inext = item + F.G;
;         if (inext < NITEM) chunk_out_load(F, inext, nxt, w, fr, fq);
	s_add_i32 s6, s10, s77
	s_cmpk_gt_i32 s6, 0x7ff
	s_cselect_b64 s[8:9], -1, 0
	s_and_b64 vcc, exec, s[8:9]
	s_cbranch_vccnz .LBB0_1676
	s_ashr_i32 s7, s6, 31
	s_lshl_b64 s[14:15], s[6:7], 13
	v_lshl_add_u64 v[16:17], v[62:63], 0, s[14:15]
	v_lshl_add_u64 v[22:23], v[16:17], 0, v[56:57]
	v_lshl_add_u64 v[18:19], v[64:65], 0, s[14:15]
	v_lshl_add_u64 v[20:21], v[66:67], 0, s[14:15]
	global_load_dwordx4 v[0:3], v[22:23], off
	global_load_dwordx4 v[4:7], v[22:23], off offset:64
	global_load_dwordx4 v[8:11], v[18:19], off
	global_load_dwordx4 v[12:15], v[18:19], off offset:64
	global_load_dwordx2 v[70:71], v[20:21], off
	global_load_dwordx2 v[72:73], v[20:21], off offset:32
	v_mov_b32_e32 v69, v57
	v_lshl_add_u64 v[92:93], v[16:17], 0, v[68:69]
	global_load_dwordx4 v[16:19], v[92:93], off
	global_load_dwordx4 v[20:23], v[92:93], off offset:64
	v_lshl_add_u64 v[114:115], v[58:59], 0, s[14:15]
	global_load_dwordx4 v[104:107], v[114:115], off
	v_lshl_add_u64 v[114:115], v[60:61], 0, s[14:15]
	global_load_dwordx4 v[108:111], v[114:115], off
	s_lshr_b32 s99, s6, 6
	s_and_b32 s99, s99, 7
	s_lshl_b32 s99, s99, 6
	v_add_lshl_u32 v116, v208, s99, 2
	v_mov_b32_e32 v117, 0
	v_lshl_add_u64 v[114:115], s[0:1], 0, v[116:117]
	global_load_dword v112, v[114:115], off
	v_lshl_add_u64 v[114:115], s[2:3], 0, v[116:117]
	global_load_dword v113, v[114:115], off
	s_cmp_eq_u32 s100, 0
	s_cbranch_scc1 .Lp7_body
	s_mov_b32 s100, 0
	s_waitcnt vmcnt(16)
	s_branch .Lp7_body
